# v17 + P0: rope-table entries and KSUM zeroing of workgroups 0..15 (the last to reach the first seam) computed by workgroups 128..143 instead
# speedup vs baseline: 1.0084x; 1.0021x over previous
; __device__ __forceinline__ void phase_prep(const Params& p, LAS unsigned char* lds) {
;     ...
;         float* COS = (float*)(p.ws + WS_COS); float* SIN = (float*)(p.ws + WS_SIN); float* KSUM = (float*)(p.ws + WS_KSUM);
;         for (int i = bid * 512 + tid; i < SEQ * 32; i += G * 512) {
;             const int pos = i >> 5, f = i & 31;
;             const float inv = 1.0f / powf(10000.0f, (float)f * (1.f / 32.f));
;             const float ang = (float)pos * inv; float sn, cs; sincosf(ang, &sn, &cs);
;             COS[i] = cs; SIN[i] = sn;
;         }
;         for (int i = bid * 512 + tid; i < 4096; i += G * 512) KSUM[i] = 0.f;
.LBB0_69:
	s_or_b64 exec, exec, s[4:5]
	s_mov_b32 s98, s2
	s_sub_i32 s99, s2, 0x80
	s_cmp_lt_u32 s99, 16
	s_cselect_b32 s98, s99, s98
	s_cmp_lt_u32 s2, 16
	s_cselect_b32 s98, 0x80, s98
	v_lshl_or_b32 v2, s98, 9, v0
	s_mov_b32 s1, 0x10000
	v_cmp_gt_i32_e32 vcc, s1, v2
	s_and_saveexec_b64 s[10:11], vcc
	v_readlane_b32 s78, v255, 0
	s_mov_b32 s81, s46
	v_readlane_b32 s79, v255, 1
	s_cbranch_execz .LBB0_76
	v_cvt_f32_ubyte0_e32 v1, v212
	v_mul_f32_e32 v1, 0x3d000000, v1
	v_mov_b32_e32 v3, 0x461c4000
	v_cmp_eq_f32_e32 vcc, 0, v1
	s_mov_b32 s1, 0x3f2aaaab
	s_mov_b32 s4, 0x42b17218
	v_cndmask_b32_e64 v3, v3, 1.0, vcc
	v_frexp_mant_f32_e32 v4, v3
	v_cmp_gt_f32_e32 vcc, s1, v4
	s_mov_b32 s1, 0x3f317218
	s_mov_b32 s5, 0x3fb8aa3b
	v_cndmask_b32_e64 v5, 1.0, 2.0, vcc
	v_mul_f32_e32 v4, v4, v5
	v_add_f32_e32 v7, 1.0, v4
	v_rcp_f32_e32 v12, v7
	v_add_f32_e32 v5, -1.0, v7
	v_sub_f32_e32 v9, v4, v5
	v_add_f32_e32 v5, -1.0, v4
	v_mul_f32_e32 v13, v5, v12
	v_mul_f32_e32 v6, v7, v13
	v_fma_f32 v8, v13, v7, -v6
	v_fmac_f32_e32 v8, v13, v9
	v_add_f32_e32 v4, v6, v8
	v_sub_f32_e32 v7, v5, v4
	v_pk_add_f32 v[10:11], v[4:5], v[6:7] neg_lo:[0,1] neg_hi:[0,1]
	v_mov_b32_e32 v9, v4
	v_pk_add_f32 v[4:5], v[10:11], v[8:9] neg_lo:[0,1] neg_hi:[0,1]
	v_mov_b32_e32 v8, 0x3e91f4c4
	v_add_f32_e32 v4, v4, v5
	v_add_f32_e32 v4, v7, v4
	v_mul_f32_e32 v5, v12, v4
	v_add_f32_e32 v4, v13, v5
	v_sub_f32_e32 v6, v4, v13
	v_sub_f32_e32 v14, v5, v6
	v_mul_f32_e32 v5, v4, v4
	v_fma_f32 v7, v4, v4, -v5
	v_add_f32_e32 v6, v14, v14
	v_fmac_f32_e32 v7, v4, v6
	v_add_f32_e32 v6, v5, v7
	v_fmac_f32_e32 v8, 0x3e76c4e1, v6
	v_fmaak_f32 v8, v6, v8, 0x3ecccdef
	v_sub_f32_e32 v5, v6, v5
	v_sub_f32_e32 v15, v7, v5
	v_mul_f32_e32 v5, v6, v8
	v_fma_f32 v7, v6, v8, -v5
	v_fmac_f32_e32 v7, v15, v8
	v_add_f32_e32 v8, v5, v7
	v_add_f32_e32 v9, 0x3f2aaaaa, v8
	v_sub_f32_e32 v5, v8, v5
	v_sub_f32_e32 v5, v7, v5
	v_add_f32_e32 v7, 0xbf2aaaaa, v9
	v_add_f32_e32 v5, 0x31739010, v5
	v_sub_f32_e32 v7, v8, v7
	v_pk_mul_f32 v[10:11], v[4:5], v[6:7]
	v_pk_add_f32 v[12:13], v[4:5], v[6:7]
	v_fma_f32 v8, v6, v4, -v10
	v_fmac_f32_e32 v8, v6, v14
	v_mov_b32_e32 v11, v13
	v_fmac_f32_e32 v8, v15, v4
	v_pk_add_f32 v[6:7], v[10:11], v[8:9]
	s_mov_b32 s3, 0x7f800000
	v_sub_f32_e32 v5, v6, v10
	v_sub_f32_e32 v5, v8, v5
	v_sub_f32_e32 v8, v9, v7
	v_add_f32_e32 v11, v13, v8
	v_cvt_f64_f32_e32 v[12:13], v3
	v_frexp_exp_i32_f64_e32 v3, v[12:13]
	v_subbrev_co_u32_e32 v3, vcc, 0, v3, vcc
	v_cvt_f32_i32_e32 v3, v3
	v_pk_mul_f32 v[8:9], v[6:7], v[6:7] op_sel:[0,1] op_sel_hi:[1,0]
	v_ldexp_f32 v13, v4, 1
	v_fma_f32 v10, v6, v7, -v8
	v_fmac_f32_e32 v10, v6, v11
	v_mul_f32_e32 v6, 0x3f317218, v3
	v_fmac_f32_e32 v10, v5, v7
	v_fma_f32 v5, v3, s1, -v6
	v_fmamk_f32 v12, v3, 0xb102e308, v5
	v_add_f32_e32 v7, v8, v10
	v_pk_add_f32 v[4:5], v[6:7], v[12:13]
	v_ldexp_f32 v3, v14, 1
	v_mov_b32_e32 v14, v7
	v_mov_b32_e32 v15, v5
	v_mov_b32_e32 v9, v13
	v_pk_add_f32 v[8:9], v[14:15], v[8:9] neg_lo:[0,1] neg_hi:[0,1]
	v_mov_b32_e32 v11, v7
	v_pk_add_f32 v[8:9], v[10:11], v[8:9] neg_lo:[0,1] neg_hi:[0,1]
	v_mov_b32_e32 v13, v4
	v_add_f32_e32 v3, v3, v8
	v_add_f32_e32 v7, v3, v9
	v_pk_add_f32 v[8:9], v[4:5], v[6:7] neg_lo:[0,1] neg_hi:[0,1]
	v_pk_add_f32 v[10:11], v[4:5], v[6:7]
	v_mov_b32_e32 v6, v7
	v_mov_b32_e32 v9, v11
	v_pk_add_f32 v[14:15], v[12:13], v[8:9] neg_lo:[0,1] neg_hi:[0,1]
	v_pk_add_f32 v[8:9], v[12:13], v[8:9]
	v_mov_b32_e32 v7, v4
	v_pk_add_f32 v[12:13], v[8:9], v[4:5] op_sel:[1,0] op_sel_hi:[0,1] neg_lo:[0,1] neg_hi:[0,1]
	v_pk_add_f32 v[16:17], v[10:11], v[12:13] op_sel_hi:[1,0] neg_lo:[0,1] neg_hi:[0,1]
	v_mov_b32_e32 v10, v11
	v_mov_b32_e32 v11, v9
	v_pk_mov_b32 v[12:13], v[4:5], v[12:13] op_sel:[1,0]
	v_mov_b32_e32 v16, v14
	v_pk_add_f32 v[10:11], v[10:11], v[12:13] neg_lo:[0,1] neg_hi:[0,1]
	v_mov_b32_e32 v15, v9
	v_pk_add_f32 v[4:5], v[6:7], v[10:11] neg_lo:[0,1] neg_hi:[0,1]
	s_movk_i32 s1, 0x204
	v_pk_add_f32 v[6:7], v[16:17], v[4:5]
	s_mov_b64 s[14:15], 0
	v_pk_add_f32 v[10:11], v[6:7], v[6:7] op_sel:[0,1] op_sel_hi:[1,0]
	s_mov_b32 s20, 0x3c439041
	v_pk_add_f32 v[8:9], v[8:9], v[10:11] op_sel:[1,0] op_sel_hi:[0,1]
	v_mov_b32_e32 v7, v8
	v_pk_add_f32 v[12:13], v[6:7], v[14:15] neg_lo:[0,1] neg_hi:[0,1]
	v_mov_b32_e32 v5, v10
	v_sub_f32_e32 v3, v6, v12
	v_pk_add_f32 v[4:5], v[4:5], v[12:13] neg_lo:[0,1] neg_hi:[0,1]
	v_sub_f32_e32 v3, v14, v3
	v_add_f32_e32 v3, v4, v3
	v_add_f32_e32 v3, v3, v5
	v_add_f32_e32 v4, v8, v3
	v_sub_f32_e32 v5, v4, v8
	v_sub_f32_e32 v3, v3, v5
	v_mul_f32_e32 v5, v1, v4
	v_fma_f32 v4, v1, v4, -v5
	v_fmac_f32_e32 v4, v1, v3
	v_add_f32_e32 v3, v5, v4
	v_cmp_class_f32_e64 vcc, v5, s1
	v_sub_f32_e32 v6, v3, v5
	v_sub_f32_e32 v4, v4, v6
	v_cndmask_b32_e32 v3, v3, v5, vcc
	v_mov_b32_e32 v5, 0x37000000
	v_cmp_eq_f32_e32 vcc, s4, v3
	s_mov_b32 s21, 0xdb629599
	s_mov_b32 s22, 0xf534ddc0
	v_cndmask_b32_e32 v5, 0, v5, vcc
	v_sub_f32_e32 v6, v3, v5
	v_mul_f32_e32 v7, 0x3fb8aa3b, v6
	v_fma_f32 v8, v6, s5, -v7
	v_rndne_f32_e32 v9, v7
	v_fmamk_f32 v8, v6, 0x32a5705f, v8
	v_sub_f32_e32 v7, v7, v9
	v_add_f32_e32 v7, v7, v8
	v_exp_f32_e32 v7, v7
	v_cvt_i32_f32_e32 v8, v9
	v_cmp_neq_f32_e64 vcc, |v3|, s3
	s_mov_b32 s5, 0xc2ce8ed0
	s_mov_b32 s23, 0xfc2757d1
	v_cndmask_b32_e32 v3, 0, v4, vcc
	v_ldexp_f32 v4, v7, v8
	v_cmp_ngt_f32_e32 vcc, s5, v6
	v_add_f32_e32 v3, v5, v3
	v_mov_b32_e32 v5, 0x7f800000
	v_cndmask_b32_e32 v4, 0, v4, vcc
	v_cmp_nlt_f32_e32 vcc, s4, v6
	s_mov_b32 s24, 0x4e441529
	s_mov_b32 s25, 0xa2f9836e
	v_cndmask_b32_e32 v4, v5, v4, vcc
	v_fma_f32 v3, v4, v3, v4
	v_cmp_class_f32_e64 vcc, v4, s1
	s_brev_b32 s1, 18
	s_mov_b32 s26, 0x3fc90fda
	v_cndmask_b32_e32 v3, v3, v4, vcc
	v_and_b32_e32 v4, 0x7fffffff, v3
	v_div_scale_f32 v5, s[4:5], v4, v4, 1.0
	v_rcp_f32_e32 v6, v5
	v_div_scale_f32 v4, vcc, 1.0, v4, 1.0
	s_mov_b64 s[4:5], 0x3320000
	v_fma_f32 v7, -v5, v6, 1.0
	v_fmac_f32_e32 v6, v7, v6
	v_mul_f32_e32 v7, v4, v6
	v_fma_f32 v8, -v5, v7, v4
	v_fmac_f32_e32 v7, v8, v6
	v_fma_f32 v4, -v5, v7, v4
	v_div_fmas_f32 v4, v4, v6, v7
	v_div_fixup_f32 v3, v4, |v3|, 1.0
	v_cmp_neq_f32_e32 vcc, s3, v1
	s_mov_b32 s3, 0xfe5163ab
	v_mov_b32_e32 v7, 0
	v_cndmask_b32_e32 v1, 0, v3, vcc
	v_ashrrev_i32_e32 v3, 31, v2
	v_lshl_add_u64 v[4:5], v[2:3], 2, s[78:79]
	v_lshl_add_u64 v[4:5], v[4:5], 0, s[4:5]
	s_mov_b32 s27, 0x3f22f983
	s_mov_b32 s28, 0xbfc90fda
	v_mov_b32_e32 v3, 0x3c0881c4
	v_mov_b32_e32 v8, 0xbab64f3b
	s_brev_b32 s29, 1
	s_movk_i32 s30, 0x1f8
	s_mov_b64 s[16:17], 0x80000
	s_mov_b32 s31, 0xfffeffff
	v_not_b32_e32 v9, 63
	v_not_b32_e32 v10, 31
	v_mov_b32_e32 v11, 0x7fc00000
	v_mov_b32_e32 v12, v2
	s_branch .LBB0_72
